# v6 + hgrn head start (7 chunks) during gdnpre + XCD-contiguous mixpre row remap
# speedup vs baseline: 1.0066x; 1.0017x over previous
.Lxr_do:
	s_and_b32 s101, s62, 7
	s_lshl_b32 s101, s101, 5
	s_lshr_b32 s64, s62, 3
	s_add_u32 s64, s64, s101
.Lxr_done:
	s_movk_i32 s101, 0x7fff
	s_cmp_eq_u32 s2, 4
	s_cbranch_scc1 .Lhs_p3
	s_cmp_eq_u32 s2, 15
	s_cbranch_scc1 .Lhs_p3
	s_branch .Lhs_done
.Lhs_p3:
	s_movk_i32 s101, 7
	s_cmp_lt_u32 s62, 64
	s_cbranch_scc1 .Lhs_done
	s_sub_u32 s64, s62, 64
	s_movk_i32 s75, 0xc0
